# v27_tbfast
# baseline (speedup 1.0000x reference)
; __device__ void attn_item(const Params& p, int id) {
;     ...
;   const int g = id >> 10, rem = id & 1023, h = rem & 7, tb = rem >> 3;
;   int seq, local;
;   if (tb < 64) { seq = tb >> 4; local = tb & 15; } else { seq = 4; local = tb - 64; }
;   const int dsh = g * 2, d = 1 << dsh;
;   const int start = seq_start(seq), len = seq_len(seq), L = len >> dsh, nub = L >> 7;
;   const int r = local / nub, ub = local % nub, u0 = ub * 128;
; __device__ void phase2(const Params& p, const int rep) {
;     ...
;     if (threadIdx.x == 0) *sid = atomicAdd(p.counters + rep, 1);
;     __syncthreads();
;     int id = *sid;
;     __syncthreads();
;     if (id >= 3072) break;
;     attn_item(p, 3071 - id);
.Lat_have:
	s_lshr_b32 s5, s4, 6
	s_and_b32 s4, s4, 63
	s_lshl_b32 s5, s5, 9
	s_or_b32 s4, s4, s5
	s_lshl_b32 s5, s98, 6
	s_or_b32 s4, s4, s5
	s_and_b32 s5, s4, 7
	s_lshr_b32 s6, s4, 3
	s_and_b32 s6, s6, 7
	s_lshl_b32 s5, s5, 3
	s_andn2_b32 s4, s4, 63
	s_or_b32 s4, s4, s5
	s_or_b32 s4, s4, s6
	s_sub_i32 s4, 0xbff, s4
	s_bfe_u32 s6, s4, 0x70003
	s_lshr_b32 s8, s4, 10
	s_and_b32 s47, s4, 7
	v_sub_co_u32_e64 v0, s[0:1], s6, 64
	s_bfe_u32 s7, s4, 0x40003
	s_and_b64 s[4:5], s[0:1], exec
	v_readfirstlane_b32 s4, v0
	s_cselect_b32 s7, s7, s4
	s_min_u32 s4, s6, 64
	s_lshl_b32 s4, s4, 7
	s_lshl_b32 s6, s8, 1
	s_and_b32 s56, s4, 0x3800
	s_and_b64 s[4:5], s[0:1], exec
	s_cselect_b32 s4, s3, 0x2000
	s_lshr_b32 s57, s4, s6
	s_lshr_b32 s4, s57, 7
	s_and_b64 s[0:1], s[0:1], exec
	s_cselect_b32 s0, 11, 13
	s_sub_i32 s0, s0, s6
	s_add_i32 s0, s0, 0xfff9
	s_and_b32 s1, s7, 0xff
	s_add_i32 s4, s4, -1
	s_lshr_b32 s5, s1, s0
	s_and_b32 s0, s4, s7
	s_lshl_b32 s0, s0, 7
	s_and_b32 s7, s0, 0x7f80
	s_mul_i32 s0, s8, 0xc00
	s_mov_b32 s1, s9
	s_lshl_b64 s[0:1], s[0:1], 1
	s_add_u32 s0, s74, s0
	s_addc_u32 s1, s75, s1
	s_lshl_b32 s4, s47, 8
	v_mov_b32_e32 v79, v248
	s_add_u32 s0, s0, s4
	s_addc_u32 s1, s1, 0
	v_and_b32_e32 v80, 15, v79
	v_ashrrev_i32_e32 v81, 4, v79
	s_sub_i32 s4, s7, 64
	v_lshl_add_u32 v37, v81, 3, s4
	v_lshlrev_b32_e32 v64, 4, v80
	s_or_b32 s58, s56, s5
	v_lshl_add_u64 v[66:67], s[0:1], 0, v[64:65]
	v_cmp_gt_u32_e32 vcc, s57, v37
	v_mov_b32_e32 v0, 0
	v_mov_b32_e32 v4, 0
	v_mov_b32_e32 v5, 0
	v_mov_b32_e32 v6, 0
	v_mov_b32_e32 v7, 0
	v_mov_b32_e32 v16, 0
	v_mov_b32_e32 v17, 0
	v_mov_b32_e32 v18, 0
	v_mov_b32_e32 v19, 0
	s_and_saveexec_b64 s[4:5], vcc
	s_cbranch_execz .LBB0_458
	v_lshlrev_b32_e32 v1, s6, v37
	v_add_u32_e32 v2, s58, v1
	v_ashrrev_i32_e32 v3, 31, v2
	v_lshlrev_b64 v[2:3], 15, v[2:3]
	v_lshl_add_u64 v[2:3], v[66:67], 0, v[2:3]
	v_add_co_u32_e32 v4, vcc, 0x1000, v2
	s_nop 1
	v_addc_co_u32_e32 v5, vcc, 0, v3, vcc
	global_load_dwordx4 v[16:19], v[2:3], off offset:2048
	s_nop 0
	global_load_dwordx4 v[4:7], v[4:5], off
